# c17 plus two wait states between the causal-mask compares and the dependent v_cndmask (hazard safety after removing the scalar AND chain)
# baseline (speedup 1.0000x reference)
.LBB0_1312:
	v_bfe_u32 v176, v32, 5, 1
	v_lshlrev_b32_e32 v172, 2, v176
	v_sub_u32_e32 v178, v0, v172
	s_add_i32 s0, 0, 0x10800
	v_bitop3_b32 v0, v176, v32, 15 bitop3:0x78
	v_writelane_b32 v254, s8, 44
	s_add_i32 s78, s75, 31
	v_lshl_add_u32 v190, v176, 4, s0
	v_lshlrev_b32_e32 v33, 8, v171
	v_lshlrev_b32_e32 v66, 4, v0
	v_or_b32_e32 v50, v66, v33
	s_setprio 1
	s_add_i32 s63, s80, 3
	v_lshl_add_u32 v16, s63, 8, v190
	ds_read_b128 v[0:3], v16
	ds_read_b128 v[4:7], v16 offset:32
	ds_read_b128 v[8:11], v16 offset:64
	ds_read_b128 v[12:15], v16 offset:96
	ds_read_b128 v[34:37], v16 offset:128
	ds_read_b128 v[38:41], v16 offset:160
	ds_read_b128 v[42:45], v16 offset:192
	ds_read_b128 v[46:49], v16 offset:224
	s_lshl_b32 s2, s63, 6
	s_waitcnt lgkmcnt(4)
	v_pk_add_f32 v[30:31], v[14:15], v[180:181] op_sel:[0,1] op_sel_hi:[1,1] neg_lo:[0,1] neg_hi:[0,1]
	v_pk_add_f32 v[28:29], v[12:13], v[180:181] op_sel:[0,1] op_sel_hi:[1,1] neg_lo:[0,1] neg_hi:[0,1]
	v_pk_add_f32 v[26:27], v[10:11], v[180:181] op_sel:[0,1] op_sel_hi:[1,1] neg_lo:[0,1] neg_hi:[0,1]
	v_pk_add_f32 v[24:25], v[8:9], v[180:181] op_sel:[0,1] op_sel_hi:[1,1] neg_lo:[0,1] neg_hi:[0,1]
	v_pk_add_f32 v[22:23], v[6:7], v[180:181] op_sel:[0,1] op_sel_hi:[1,1] neg_lo:[0,1] neg_hi:[0,1]
	v_pk_add_f32 v[20:21], v[4:5], v[180:181] op_sel:[0,1] op_sel_hi:[1,1] neg_lo:[0,1] neg_hi:[0,1]
	v_pk_add_f32 v[18:19], v[2:3], v[180:181] op_sel:[0,1] op_sel_hi:[1,1] neg_lo:[0,1] neg_hi:[0,1]
	v_pk_add_f32 v[16:17], v[0:1], v[180:181] op_sel:[0,1] op_sel_hi:[1,1] neg_lo:[0,1] neg_hi:[0,1]
	s_waitcnt lgkmcnt(0)
	v_pk_add_f32 v[14:15], v[48:49], v[180:181] op_sel:[0,1] op_sel_hi:[1,1] neg_lo:[0,1] neg_hi:[0,1]
	v_pk_add_f32 v[12:13], v[46:47], v[180:181] op_sel:[0,1] op_sel_hi:[1,1] neg_lo:[0,1] neg_hi:[0,1]
	v_pk_add_f32 v[10:11], v[44:45], v[180:181] op_sel:[0,1] op_sel_hi:[1,1] neg_lo:[0,1] neg_hi:[0,1]
	v_pk_add_f32 v[8:9], v[42:43], v[180:181] op_sel:[0,1] op_sel_hi:[1,1] neg_lo:[0,1] neg_hi:[0,1]
	v_pk_add_f32 v[6:7], v[40:41], v[180:181] op_sel:[0,1] op_sel_hi:[1,1] neg_lo:[0,1] neg_hi:[0,1]
	v_pk_add_f32 v[4:5], v[38:39], v[180:181] op_sel:[0,1] op_sel_hi:[1,1] neg_lo:[0,1] neg_hi:[0,1]
	v_pk_add_f32 v[2:3], v[36:37], v[180:181] op_sel:[0,1] op_sel_hi:[1,1] neg_lo:[0,1] neg_hi:[0,1]
	v_pk_add_f32 v[0:1], v[34:35], v[180:181] op_sel:[0,1] op_sel_hi:[1,1] neg_lo:[0,1] neg_hi:[0,1]
	s_cmp_lg_u32 0, -1
	s_cselect_b32 s0, 0, 0
	v_add_u32_e32 v189, s0, v50
	ds_read_b128 v[34:37], v189 offset:0x8000
	ds_read_b128 v[38:41], v189 offset:0xa000
	v_xad_u32 v188, v50, 32, s0
	ds_read_b128 v[42:45], v188 offset:0x8000
	ds_read_b128 v[46:49], v188 offset:0xa000
	v_xad_u32 v187, v50, 64, s0
	ds_read_b128 v[50:53], v187 offset:0x8000
	s_movk_i32 s1, 0x60
	ds_read_b128 v[54:57], v187 offset:0xa000
	v_bitop3_b32 v58, v66, s1, v33 bitop3:0x36
	v_add_u32_e32 v184, s0, v58
	ds_read_b128 v[58:61], v184 offset:0x8000
	ds_read_b128 v[62:65], v184 offset:0xa000
	s_waitcnt lgkmcnt(7)
	v_mfma_f32_32x32x16_bf16 v[16:31], v[34:37], v[144:147], v[16:31]
	s_movk_i32 s1, 0x80
	v_bitop3_b32 v34, v66, s1, v33 bitop3:0x36
	v_add_u32_e32 v182, s0, v34
	ds_read_b128 v[34:37], v182 offset:0x8000
	s_waitcnt lgkmcnt(7)
	v_mfma_f32_32x32x16_bf16 v[0:15], v[38:41], v[144:147], v[0:15]
	ds_read_b128 v[38:41], v182 offset:0xa000
	s_waitcnt lgkmcnt(7)
	v_mfma_f32_32x32x16_bf16 v[16:31], v[42:45], v[136:139], v[16:31]
	s_movk_i32 s1, 0xa0
	v_bitop3_b32 v42, v66, s1, v33 bitop3:0x36
	v_add_u32_e32 v183, s0, v42
	ds_read_b128 v[42:45], v183 offset:0x8000
	s_waitcnt lgkmcnt(7)
	v_mfma_f32_32x32x16_bf16 v[0:15], v[46:49], v[136:139], v[0:15]
	ds_read_b128 v[46:49], v183 offset:0xa000
	s_waitcnt lgkmcnt(7)
	v_mfma_f32_32x32x16_bf16 v[16:31], v[50:53], v[128:131], v[16:31]
	s_movk_i32 s1, 0xc0
	v_bitop3_b32 v50, v66, s1, v33 bitop3:0x36
	v_add_u32_e32 v185, s0, v50
	ds_read_b128 v[50:53], v185 offset:0x8000
	s_waitcnt lgkmcnt(7)
	v_mfma_f32_32x32x16_bf16 v[0:15], v[54:57], v[128:131], v[0:15]
	ds_read_b128 v[54:57], v185 offset:0xa000
	s_waitcnt lgkmcnt(7)
	v_mfma_f32_32x32x16_bf16 v[16:31], v[58:61], v[124:127], v[16:31]
	s_movk_i32 s1, 0xe0
	v_bitop3_b32 v33, v66, s1, v33 bitop3:0x36
	v_add_u32_e32 v186, s0, v33
	ds_read_b128 v[58:61], v186 offset:0x8000
	s_waitcnt lgkmcnt(7)
	v_mfma_f32_32x32x16_bf16 v[0:15], v[62:65], v[124:127], v[0:15]
	ds_read_b128 v[62:65], v186 offset:0xa000
	s_waitcnt lgkmcnt(7)
	v_mfma_f32_32x32x16_bf16 v[16:31], v[34:37], v[120:123], v[16:31]
	s_waitcnt lgkmcnt(6)
	v_mfma_f32_32x32x16_bf16 v[0:15], v[38:41], v[120:123], v[0:15]
	s_waitcnt lgkmcnt(5)
	v_mfma_f32_32x32x16_bf16 v[16:31], v[42:45], v[116:119], v[16:31]
	s_waitcnt lgkmcnt(4)
	v_mfma_f32_32x32x16_bf16 v[0:15], v[46:49], v[116:119], v[0:15]
	s_waitcnt lgkmcnt(3)
	s_waitcnt vmcnt(1)
	v_mfma_f32_32x32x16_bf16 v[16:31], v[50:53], v[140:143], v[16:31]
	s_waitcnt lgkmcnt(2)
	v_mfma_f32_32x32x16_bf16 v[0:15], v[54:57], v[140:143], v[0:15]
	s_waitcnt lgkmcnt(1)
	s_waitcnt vmcnt(0)
	v_mfma_f32_32x32x16_bf16 v[16:31], v[58:61], v[132:135], v[16:31]
	s_waitcnt lgkmcnt(0)
	v_mfma_f32_32x32x16_bf16 v[0:15], v[62:65], v[132:135], v[0:15]
	s_setprio 0
	s_waitcnt lgkmcnt(0)
	s_barrier
	s_cmp_le_i32 s2, s78
	s_mov_b64 s[0:1], -1
	s_cbranch_scc0 .LBB0_1316
	s_or_b32 s0, s2, 63
	s_cmp_le_u32 s0, s75
	s_cbranch_scc1 .LBB0_1315
	v_subrev_u32_e32 v33, s2, v178
	v_cmp_gt_i32_e64 s[58:59], 26, v33
	v_cmp_gt_i32_e64 s[60:61], 27, v33
	v_cmp_gt_i32_e64 s[56:57], 25, v33
	v_cmp_gt_i32_e64 s[54:55], 24, v33
	v_cmp_gt_i32_e64 s[52:53], 19, v33
	v_cmp_gt_i32_e64 s[50:51], 18, v33
	v_cmp_gt_i32_e64 s[48:49], 17, v33
	v_cmp_gt_i32_e64 s[46:47], 16, v33
	v_cmp_gt_i32_e64 s[44:45], 11, v33
	v_cmp_gt_i32_e64 s[42:43], 10, v33
	v_cmp_gt_i32_e64 s[40:41], 9, v33
	v_cmp_gt_i32_e64 s[38:39], 8, v33
	v_cmp_gt_i32_e64 s[36:37], 3, v33
	v_cmp_gt_i32_e64 s[34:35], 2, v33
	v_cmp_gt_i32_e64 s[30:31], 1, v33
	v_cmp_gt_i32_e64 s[28:29], 0, v33
	v_cmp_gt_i32_e64 s[26:27], 58, v33
	s_nop 1
	v_cndmask_b32_e64 v16, v16, v169, s[28:29]
	v_cmp_gt_i32_e64 s[28:29], 59, v33
	v_cmp_gt_i32_e64 s[24:25], 57, v33
	v_cmp_gt_i32_e64 s[22:23], 56, v33
	v_cmp_gt_i32_e64 s[20:21], 51, v33
	v_cmp_gt_i32_e64 s[18:19], 50, v33
	v_cmp_gt_i32_e64 s[16:17], 49, v33
	v_cmp_gt_i32_e64 s[14:15], 48, v33
	v_cmp_gt_i32_e64 s[12:13], 43, v33
	v_cmp_gt_i32_e64 s[10:11], 42, v33
	v_cmp_gt_i32_e64 s[8:9], 41, v33
	v_cmp_gt_i32_e64 s[6:7], 40, v33
	v_cmp_gt_i32_e64 s[4:5], 35, v33
	v_cmp_gt_i32_e64 s[2:3], 34, v33
	v_cmp_gt_i32_e64 s[0:1], 33, v33
	v_cmp_gt_i32_e32 vcc, 32, v33
	v_cndmask_b32_e64 v31, v31, v169, s[60:61]
	v_cndmask_b32_e64 v30, v30, v169, s[58:59]
	v_cndmask_b32_e64 v29, v29, v169, s[56:57]
	v_cndmask_b32_e64 v28, v28, v169, s[54:55]
	v_cndmask_b32_e64 v27, v27, v169, s[52:53]
	v_cndmask_b32_e64 v26, v26, v169, s[50:51]
	v_cndmask_b32_e64 v25, v25, v169, s[48:49]
	v_cndmask_b32_e64 v24, v24, v169, s[46:47]
	v_cndmask_b32_e64 v23, v23, v169, s[44:45]
	v_cndmask_b32_e64 v22, v22, v169, s[42:43]
	v_cndmask_b32_e64 v21, v21, v169, s[40:41]
	v_cndmask_b32_e64 v20, v20, v169, s[38:39]
	v_cndmask_b32_e64 v19, v19, v169, s[36:37]
	v_cndmask_b32_e64 v18, v18, v169, s[34:35]
	v_cndmask_b32_e64 v17, v17, v169, s[30:31]
	v_cndmask_b32_e64 v15, v15, v169, s[28:29]
	v_cndmask_b32_e64 v14, v14, v169, s[26:27]
	v_cndmask_b32_e64 v13, v13, v169, s[24:25]
	v_cndmask_b32_e64 v12, v12, v169, s[22:23]
	v_cndmask_b32_e64 v11, v11, v169, s[20:21]
	v_cndmask_b32_e64 v10, v10, v169, s[18:19]
	v_cndmask_b32_e64 v9, v9, v169, s[16:17]
	v_cndmask_b32_e64 v8, v8, v169, s[14:15]
	v_cndmask_b32_e64 v7, v7, v169, s[12:13]
	v_cndmask_b32_e64 v6, v6, v169, s[10:11]
	v_cndmask_b32_e64 v5, v5, v169, s[8:9]
	v_cndmask_b32_e64 v4, v4, v169, s[6:7]
	v_cndmask_b32_e64 v3, v3, v169, s[4:5]
	v_cndmask_b32_e64 v2, v2, v169, s[2:3]
	v_cndmask_b32_e64 v1, v1, v169, s[0:1]
	v_cndmask_b32_e32 v0, v0, v169, vcc
	s_nop 0

.LBB0_1328:
	s_setprio 1
	ds_read_b128 v[64:67], v194 offset:256
	ds_read_b128 v[68:71], v194 offset:288
	ds_read_b128 v[72:75], v194 offset:320
	ds_read_b128 v[76:79], v194 offset:352
	ds_read_b128 v[196:199], v194 offset:384
	ds_read_b128 v[200:203], v194 offset:416
	ds_read_b128 v[204:207], v194 offset:448
	ds_read_b128 v[208:211], v194 offset:480
	s_add_i32 s0, s84, 64
	s_waitcnt lgkmcnt(4)
	v_pk_add_f32 v[94:95], v[78:79], v[180:181] op_sel:[0,1] op_sel_hi:[1,1] neg_lo:[0,1] neg_hi:[0,1]
	v_pk_add_f32 v[92:93], v[76:77], v[180:181] op_sel:[0,1] op_sel_hi:[1,1] neg_lo:[0,1] neg_hi:[0,1]
	v_pk_add_f32 v[90:91], v[74:75], v[180:181] op_sel:[0,1] op_sel_hi:[1,1] neg_lo:[0,1] neg_hi:[0,1]
	v_pk_add_f32 v[88:89], v[72:73], v[180:181] op_sel:[0,1] op_sel_hi:[1,1] neg_lo:[0,1] neg_hi:[0,1]
	v_pk_add_f32 v[86:87], v[70:71], v[180:181] op_sel:[0,1] op_sel_hi:[1,1] neg_lo:[0,1] neg_hi:[0,1]
	v_pk_add_f32 v[84:85], v[68:69], v[180:181] op_sel:[0,1] op_sel_hi:[1,1] neg_lo:[0,1] neg_hi:[0,1]
	v_pk_add_f32 v[82:83], v[66:67], v[180:181] op_sel:[0,1] op_sel_hi:[1,1] neg_lo:[0,1] neg_hi:[0,1]
	v_pk_add_f32 v[80:81], v[64:65], v[180:181] op_sel:[0,1] op_sel_hi:[1,1] neg_lo:[0,1] neg_hi:[0,1]
	s_waitcnt lgkmcnt(0)
	v_pk_add_f32 v[78:79], v[210:211], v[180:181] op_sel:[0,1] op_sel_hi:[1,1] neg_lo:[0,1] neg_hi:[0,1]
	v_pk_add_f32 v[76:77], v[208:209], v[180:181] op_sel:[0,1] op_sel_hi:[1,1] neg_lo:[0,1] neg_hi:[0,1]
	v_pk_add_f32 v[74:75], v[206:207], v[180:181] op_sel:[0,1] op_sel_hi:[1,1] neg_lo:[0,1] neg_hi:[0,1]
	v_pk_add_f32 v[72:73], v[204:205], v[180:181] op_sel:[0,1] op_sel_hi:[1,1] neg_lo:[0,1] neg_hi:[0,1]
	v_pk_add_f32 v[70:71], v[202:203], v[180:181] op_sel:[0,1] op_sel_hi:[1,1] neg_lo:[0,1] neg_hi:[0,1]
	v_pk_add_f32 v[68:69], v[200:201], v[180:181] op_sel:[0,1] op_sel_hi:[1,1] neg_lo:[0,1] neg_hi:[0,1]
	v_pk_add_f32 v[66:67], v[198:199], v[180:181] op_sel:[0,1] op_sel_hi:[1,1] neg_lo:[0,1] neg_hi:[0,1]
	v_pk_add_f32 v[64:65], v[196:197], v[180:181] op_sel:[0,1] op_sel_hi:[1,1] neg_lo:[0,1] neg_hi:[0,1]
	ds_read_b64_tr_b16 v[196:197], v179 offset:0
	ds_read_b64_tr_b16 v[198:199], v179 offset:0x800
	ds_read_b64_tr_b16 v[200:201], v179 offset:0x1000
	ds_read_b64_tr_b16 v[202:203], v179 offset:0x1800
	ds_read_b64_tr_b16 v[204:205], v179 offset:0x2000
	ds_read_b64_tr_b16 v[206:207], v179 offset:0x2800
	ds_read_b64_tr_b16 v[208:209], v179 offset:0x3000
	ds_read_b64_tr_b16 v[210:211], v179 offset:0x3800
	ds_read_b64_tr_b16 v[212:213], v179 offset:0x200
	ds_read_b64_tr_b16 v[214:215], v179 offset:0xa00
	ds_read_b64_tr_b16 v[216:217], v179 offset:0x1200
	ds_read_b64_tr_b16 v[218:219], v179 offset:0x1a00
	ds_read_b64_tr_b16 v[220:221], v179 offset:0x2200
	ds_read_b64_tr_b16 v[222:223], v179 offset:0x2a00
	ds_read_b64_tr_b16 v[224:225], v179 offset:0x3200
	ds_read_b64_tr_b16 v[226:227], v179 offset:0x3a00
	s_waitcnt lgkmcnt(14)
	s_nop 0
	v_mfma_f32_32x32x16_bf16 v[0:15], v[160:163], v[196:199], v[0:15]
	ds_read_b64_tr_b16 v[196:197], v179 offset:0x400
	ds_read_b64_tr_b16 v[198:199], v179 offset:0xc00
	s_waitcnt lgkmcnt(14)
	v_mfma_f32_32x32x16_bf16 v[0:15], v[156:159], v[200:203], v[0:15]
	ds_read_b64_tr_b16 v[200:201], v179 offset:0x1400
	ds_read_b64_tr_b16 v[202:203], v179 offset:0x1c00
	s_waitcnt lgkmcnt(14)
	v_mfma_f32_32x32x16_bf16 v[0:15], v[152:155], v[204:207], v[0:15]
	ds_read_b64_tr_b16 v[204:205], v179 offset:0x2400
	ds_read_b64_tr_b16 v[206:207], v179 offset:0x2c00
	s_waitcnt lgkmcnt(14)
	v_mfma_f32_32x32x16_bf16 v[0:15], v[148:151], v[208:211], v[0:15]
	ds_read_b64_tr_b16 v[208:209], v179 offset:0x3400
	ds_read_b64_tr_b16 v[210:211], v179 offset:0x3c00
	s_waitcnt lgkmcnt(14)
	v_mfma_f32_32x32x16_bf16 v[48:63], v[160:163], v[212:215], v[48:63]
	ds_read_b64_tr_b16 v[212:213], v179 offset:0x600
	ds_read_b64_tr_b16 v[214:215], v179 offset:0xe00
	s_waitcnt lgkmcnt(14)
	v_mfma_f32_32x32x16_bf16 v[48:63], v[156:159], v[216:219], v[48:63]
	ds_read_b64_tr_b16 v[216:217], v179 offset:0x1600
	ds_read_b64_tr_b16 v[218:219], v179 offset:0x1e00
	s_waitcnt lgkmcnt(14)
	v_mfma_f32_32x32x16_bf16 v[48:63], v[152:155], v[220:223], v[48:63]
	ds_read_b64_tr_b16 v[220:221], v179 offset:0x2600
	ds_read_b64_tr_b16 v[222:223], v179 offset:0x2e00
	s_waitcnt lgkmcnt(14)
	v_mfma_f32_32x32x16_bf16 v[48:63], v[148:151], v[224:227], v[48:63]
	ds_read_b64_tr_b16 v[224:225], v179 offset:0x3600
	ds_read_b64_tr_b16 v[226:227], v179 offset:0x3e00
	s_waitcnt lgkmcnt(14)
	v_mfma_f32_32x32x16_bf16 v[32:47], v[160:163], v[196:199], v[32:47]
	ds_read_b128 v[196:199], v189 offset:0xc000
	s_waitcnt lgkmcnt(13)
	v_mfma_f32_32x32x16_bf16 v[32:47], v[156:159], v[200:203], v[32:47]
	ds_read_b128 v[200:203], v189 offset:0xe000
	s_waitcnt lgkmcnt(12)
	v_mfma_f32_32x32x16_bf16 v[32:47], v[152:155], v[204:207], v[32:47]
	ds_read_b128 v[204:207], v188 offset:0xc000
	s_waitcnt lgkmcnt(11)
	v_mfma_f32_32x32x16_bf16 v[32:47], v[148:151], v[208:211], v[32:47]
	ds_read_b128 v[208:211], v188 offset:0xe000
	s_waitcnt lgkmcnt(10)
	v_mfma_f32_32x32x16_bf16 v[16:31], v[160:163], v[212:215], v[16:31]
	ds_read_b128 v[160:163], v187 offset:0xc000
	s_waitcnt lgkmcnt(9)
	v_mfma_f32_32x32x16_bf16 v[16:31], v[156:159], v[216:219], v[16:31]
	ds_read_b128 v[156:159], v187 offset:0xe000
	s_waitcnt lgkmcnt(8)
	v_mfma_f32_32x32x16_bf16 v[16:31], v[152:155], v[220:223], v[16:31]
	ds_read_b128 v[152:155], v184 offset:0xc000
	s_waitcnt lgkmcnt(7)
	v_mfma_f32_32x32x16_bf16 v[16:31], v[148:151], v[224:227], v[16:31]
	ds_read_b128 v[148:151], v184 offset:0xe000
	s_waitcnt lgkmcnt(7)
	v_mfma_f32_32x32x16_bf16 v[80:95], v[196:199], v[144:147], v[80:95]
	ds_read_b128 v[196:199], v182 offset:0xc000
	s_waitcnt lgkmcnt(7)
	v_mfma_f32_32x32x16_bf16 v[64:79], v[200:203], v[144:147], v[64:79]
	ds_read_b128 v[200:203], v182 offset:0xe000
	s_waitcnt lgkmcnt(7)
	v_mfma_f32_32x32x16_bf16 v[80:95], v[204:207], v[136:139], v[80:95]
	ds_read_b128 v[204:207], v183 offset:0xc000
	s_waitcnt lgkmcnt(7)
	v_mfma_f32_32x32x16_bf16 v[64:79], v[208:211], v[136:139], v[64:79]
	ds_read_b128 v[208:211], v183 offset:0xe000
	s_waitcnt lgkmcnt(7)
	v_mfma_f32_32x32x16_bf16 v[80:95], v[160:163], v[128:131], v[80:95]
	ds_read_b128 v[160:163], v185 offset:0xc000
	s_waitcnt lgkmcnt(7)
	v_mfma_f32_32x32x16_bf16 v[64:79], v[156:159], v[128:131], v[64:79]
	ds_read_b128 v[156:159], v185 offset:0xe000
	s_waitcnt lgkmcnt(7)
	v_mfma_f32_32x32x16_bf16 v[80:95], v[152:155], v[124:127], v[80:95]
	ds_read_b128 v[152:155], v186 offset:0xc000
	s_waitcnt lgkmcnt(7)
	v_mfma_f32_32x32x16_bf16 v[64:79], v[148:151], v[124:127], v[64:79]
	ds_read_b128 v[148:151], v186 offset:0xe000
	s_waitcnt lgkmcnt(7)
	v_mfma_f32_32x32x16_bf16 v[80:95], v[196:199], v[120:123], v[80:95]
	s_waitcnt lgkmcnt(6)
	v_mfma_f32_32x32x16_bf16 v[64:79], v[200:203], v[120:123], v[64:79]
	s_waitcnt lgkmcnt(5)
	v_mfma_f32_32x32x16_bf16 v[80:95], v[204:207], v[116:119], v[80:95]
	s_waitcnt lgkmcnt(4)
	v_mfma_f32_32x32x16_bf16 v[64:79], v[208:211], v[116:119], v[64:79]
	s_waitcnt lgkmcnt(3)
	v_mfma_f32_32x32x16_bf16 v[80:95], v[160:163], v[140:143], v[80:95]
	s_waitcnt lgkmcnt(2)
	v_mfma_f32_32x32x16_bf16 v[64:79], v[156:159], v[140:143], v[64:79]
	s_waitcnt lgkmcnt(1)
	v_mfma_f32_32x32x16_bf16 v[80:95], v[152:155], v[132:135], v[80:95]
	s_waitcnt lgkmcnt(0)
	v_mfma_f32_32x32x16_bf16 v[64:79], v[148:151], v[132:135], v[64:79]
	s_setprio 0
	s_waitcnt lgkmcnt(0)
	s_barrier
	s_cmp_le_i32 s0, s78
	s_mov_b64 s[0:1], -1
	s_cbranch_scc0 .LBB0_1332
	s_add_i32 s0, s84, 0x7f
	s_cmp_le_i32 s0, s75
	s_cbranch_scc1 .LBB0_1331
	v_subrev_u32_e32 v97, 64, v193
	v_cmp_gt_i32_e64 s[58:59], 26, v97
	v_cmp_gt_i32_e64 s[60:61], 27, v97
	v_cmp_gt_i32_e64 s[56:57], 25, v97
	v_cmp_gt_i32_e64 s[54:55], 24, v97
	v_cmp_gt_i32_e64 s[52:53], 19, v97
	v_cmp_gt_i32_e64 s[50:51], 18, v97
	v_cmp_gt_i32_e64 s[48:49], 17, v97
	v_cmp_gt_i32_e64 s[46:47], 16, v97
	v_cmp_gt_i32_e64 s[44:45], 11, v97
	v_cmp_gt_i32_e64 s[42:43], 10, v97
	v_cmp_gt_i32_e64 s[40:41], 9, v97
	v_cmp_gt_i32_e64 s[38:39], 8, v97
	v_cmp_gt_i32_e64 s[36:37], 3, v97
	v_cmp_gt_i32_e64 s[34:35], 2, v97
	v_cmp_gt_i32_e64 s[30:31], 1, v97
	v_cmp_gt_i32_e64 s[28:29], 0, v97
	v_cmp_gt_i32_e64 s[26:27], 58, v97
	s_nop 1
	v_cndmask_b32_e64 v80, v80, v169, s[28:29]
	v_cmp_gt_i32_e64 s[28:29], 59, v97
	v_cmp_gt_i32_e64 s[24:25], 57, v97
	v_cmp_gt_i32_e64 s[22:23], 56, v97
	v_cmp_gt_i32_e64 s[20:21], 51, v97
	v_cmp_gt_i32_e64 s[18:19], 50, v97
	v_cmp_gt_i32_e64 s[16:17], 49, v97
	v_cmp_gt_i32_e64 s[14:15], 48, v97
	v_cmp_gt_i32_e64 s[12:13], 43, v97
	v_cmp_gt_i32_e64 s[10:11], 42, v97
	v_cmp_gt_i32_e64 s[8:9], 41, v97
	v_cmp_gt_i32_e64 s[6:7], 40, v97
	v_cmp_gt_i32_e64 s[4:5], 35, v97
	v_cmp_gt_i32_e64 s[2:3], 34, v97
	v_cmp_gt_i32_e64 s[0:1], 33, v97
	v_cmp_gt_i32_e32 vcc, 32, v97
	v_cndmask_b32_e64 v95, v95, v169, s[60:61]
	v_cndmask_b32_e64 v94, v94, v169, s[58:59]
	v_cndmask_b32_e64 v93, v93, v169, s[56:57]
	v_cndmask_b32_e64 v92, v92, v169, s[54:55]
	v_cndmask_b32_e64 v91, v91, v169, s[52:53]
	v_cndmask_b32_e64 v90, v90, v169, s[50:51]
	v_cndmask_b32_e64 v89, v89, v169, s[48:49]
	v_cndmask_b32_e64 v88, v88, v169, s[46:47]
	v_cndmask_b32_e64 v87, v87, v169, s[44:45]
	v_cndmask_b32_e64 v86, v86, v169, s[42:43]
	v_cndmask_b32_e64 v85, v85, v169, s[40:41]
	v_cndmask_b32_e64 v84, v84, v169, s[38:39]
	v_cndmask_b32_e64 v83, v83, v169, s[36:37]
	v_cndmask_b32_e64 v82, v82, v169, s[34:35]
	v_cndmask_b32_e64 v81, v81, v169, s[30:31]
	v_cndmask_b32_e64 v79, v79, v169, s[28:29]
	v_cndmask_b32_e64 v78, v78, v169, s[26:27]
	v_cndmask_b32_e64 v77, v77, v169, s[24:25]
	v_cndmask_b32_e64 v76, v76, v169, s[22:23]
	v_cndmask_b32_e64 v75, v75, v169, s[20:21]
	v_cndmask_b32_e64 v74, v74, v169, s[18:19]
	v_cndmask_b32_e64 v73, v73, v169, s[16:17]
	v_cndmask_b32_e64 v72, v72, v169, s[14:15]
	v_cndmask_b32_e64 v71, v71, v169, s[12:13]
	v_cndmask_b32_e64 v70, v70, v169, s[10:11]
	v_cndmask_b32_e64 v69, v69, v169, s[8:9]
	v_cndmask_b32_e64 v68, v68, v169, s[6:7]
	v_cndmask_b32_e64 v67, v67, v169, s[4:5]
	v_cndmask_b32_e64 v66, v66, v169, s[2:3]
	v_cndmask_b32_e64 v65, v65, v169, s[0:1]
	v_cndmask_b32_e32 v64, v64, v169, vcc
	s_nop 0

.LBB0_1336:
	global_load_dwordx4 v[100:103], v164, s[0:1]
	global_load_dwordx4 v[104:107], v166, s[0:1]
	global_load_dwordx4 v[112:115], v164, s[2:3]
	global_load_dwordx4 v[108:111], v166, s[2:3]
	s_waitcnt lgkmcnt(0)
	s_barrier
	s_setprio 1
	ds_read_b128 v[64:67], v194
	ds_read_b128 v[68:71], v194 offset:32
	ds_read_b128 v[72:75], v194 offset:64
	ds_read_b128 v[76:79], v194 offset:96
	ds_read_b128 v[196:199], v194 offset:128
	ds_read_b128 v[200:203], v194 offset:160
	ds_read_b128 v[204:207], v194 offset:192
	ds_read_b128 v[208:211], v194 offset:224
	s_waitcnt lgkmcnt(4)
	v_pk_add_f32 v[94:95], v[78:79], v[180:181] op_sel:[0,1] op_sel_hi:[1,1] neg_lo:[0,1] neg_hi:[0,1]
	v_pk_add_f32 v[92:93], v[76:77], v[180:181] op_sel:[0,1] op_sel_hi:[1,1] neg_lo:[0,1] neg_hi:[0,1]
	v_pk_add_f32 v[90:91], v[74:75], v[180:181] op_sel:[0,1] op_sel_hi:[1,1] neg_lo:[0,1] neg_hi:[0,1]
	v_pk_add_f32 v[88:89], v[72:73], v[180:181] op_sel:[0,1] op_sel_hi:[1,1] neg_lo:[0,1] neg_hi:[0,1]
	v_pk_add_f32 v[86:87], v[70:71], v[180:181] op_sel:[0,1] op_sel_hi:[1,1] neg_lo:[0,1] neg_hi:[0,1]
	v_pk_add_f32 v[84:85], v[68:69], v[180:181] op_sel:[0,1] op_sel_hi:[1,1] neg_lo:[0,1] neg_hi:[0,1]
	v_pk_add_f32 v[82:83], v[66:67], v[180:181] op_sel:[0,1] op_sel_hi:[1,1] neg_lo:[0,1] neg_hi:[0,1]
	v_pk_add_f32 v[80:81], v[64:65], v[180:181] op_sel:[0,1] op_sel_hi:[1,1] neg_lo:[0,1] neg_hi:[0,1]
	s_waitcnt lgkmcnt(0)
	v_pk_add_f32 v[78:79], v[210:211], v[180:181] op_sel:[0,1] op_sel_hi:[1,1] neg_lo:[0,1] neg_hi:[0,1]
	v_pk_add_f32 v[76:77], v[208:209], v[180:181] op_sel:[0,1] op_sel_hi:[1,1] neg_lo:[0,1] neg_hi:[0,1]
	v_pk_add_f32 v[74:75], v[206:207], v[180:181] op_sel:[0,1] op_sel_hi:[1,1] neg_lo:[0,1] neg_hi:[0,1]
	v_pk_add_f32 v[72:73], v[204:205], v[180:181] op_sel:[0,1] op_sel_hi:[1,1] neg_lo:[0,1] neg_hi:[0,1]
	v_pk_add_f32 v[70:71], v[202:203], v[180:181] op_sel:[0,1] op_sel_hi:[1,1] neg_lo:[0,1] neg_hi:[0,1]
	v_pk_add_f32 v[68:69], v[200:201], v[180:181] op_sel:[0,1] op_sel_hi:[1,1] neg_lo:[0,1] neg_hi:[0,1]
	v_pk_add_f32 v[66:67], v[198:199], v[180:181] op_sel:[0,1] op_sel_hi:[1,1] neg_lo:[0,1] neg_hi:[0,1]
	v_pk_add_f32 v[64:65], v[196:197], v[180:181] op_sel:[0,1] op_sel_hi:[1,1] neg_lo:[0,1] neg_hi:[0,1]
	ds_read_b64_tr_b16 v[196:197], v179 offset:0x4000
	ds_read_b64_tr_b16 v[198:199], v179 offset:0x4800
	ds_read_b64_tr_b16 v[200:201], v179 offset:0x5000
	ds_read_b64_tr_b16 v[202:203], v179 offset:0x5800
	ds_read_b64_tr_b16 v[204:205], v179 offset:0x6000
	ds_read_b64_tr_b16 v[206:207], v179 offset:0x6800
	ds_read_b64_tr_b16 v[208:209], v179 offset:0x7000
	ds_read_b64_tr_b16 v[210:211], v179 offset:0x7800
	ds_read_b64_tr_b16 v[212:213], v179 offset:0x4200
	ds_read_b64_tr_b16 v[214:215], v179 offset:0x4a00
	ds_read_b64_tr_b16 v[216:217], v179 offset:0x5200
	ds_read_b64_tr_b16 v[218:219], v179 offset:0x5a00
	ds_read_b64_tr_b16 v[220:221], v179 offset:0x6200
	ds_read_b64_tr_b16 v[222:223], v179 offset:0x6a00
	ds_read_b64_tr_b16 v[224:225], v179 offset:0x7200
	ds_read_b64_tr_b16 v[226:227], v179 offset:0x7a00
	s_waitcnt lgkmcnt(14)
	s_nop 0
	v_mfma_f32_32x32x16_bf16 v[0:15], v[160:163], v[196:199], v[0:15]
	ds_read_b64_tr_b16 v[196:197], v179 offset:0x4400
	ds_read_b64_tr_b16 v[198:199], v179 offset:0x4c00
	s_waitcnt lgkmcnt(14)
	v_mfma_f32_32x32x16_bf16 v[0:15], v[156:159], v[200:203], v[0:15]
	ds_read_b64_tr_b16 v[200:201], v179 offset:0x5400
	ds_read_b64_tr_b16 v[202:203], v179 offset:0x5c00
	s_waitcnt lgkmcnt(14)
	v_mfma_f32_32x32x16_bf16 v[0:15], v[152:155], v[204:207], v[0:15]
	ds_read_b64_tr_b16 v[204:205], v179 offset:0x6400
	ds_read_b64_tr_b16 v[206:207], v179 offset:0x6c00
	s_waitcnt lgkmcnt(14)
	v_mfma_f32_32x32x16_bf16 v[0:15], v[148:151], v[208:211], v[0:15]
	ds_read_b64_tr_b16 v[208:209], v179 offset:0x7400
	ds_read_b64_tr_b16 v[210:211], v179 offset:0x7c00
	s_waitcnt lgkmcnt(14)
	v_mfma_f32_32x32x16_bf16 v[48:63], v[160:163], v[212:215], v[48:63]
	ds_read_b64_tr_b16 v[212:213], v179 offset:0x4600
	ds_read_b64_tr_b16 v[214:215], v179 offset:0x4e00
	s_waitcnt lgkmcnt(14)
	v_mfma_f32_32x32x16_bf16 v[48:63], v[156:159], v[216:219], v[48:63]
	ds_read_b64_tr_b16 v[216:217], v179 offset:0x5600
	ds_read_b64_tr_b16 v[218:219], v179 offset:0x5e00
	s_waitcnt lgkmcnt(14)
	v_mfma_f32_32x32x16_bf16 v[48:63], v[152:155], v[220:223], v[48:63]
	ds_read_b64_tr_b16 v[220:221], v179 offset:0x6600
	ds_read_b64_tr_b16 v[222:223], v179 offset:0x6e00
	s_waitcnt lgkmcnt(14)
	v_mfma_f32_32x32x16_bf16 v[48:63], v[148:151], v[224:227], v[48:63]
	ds_read_b64_tr_b16 v[224:225], v179 offset:0x7600
	ds_read_b64_tr_b16 v[226:227], v179 offset:0x7e00
	s_waitcnt lgkmcnt(14)
	v_mfma_f32_32x32x16_bf16 v[32:47], v[160:163], v[196:199], v[32:47]
	ds_read_b128 v[196:199], v189 offset:0x8000
	s_waitcnt lgkmcnt(13)
	v_mfma_f32_32x32x16_bf16 v[32:47], v[156:159], v[200:203], v[32:47]
	ds_read_b128 v[200:203], v189 offset:0xa000
	s_waitcnt lgkmcnt(12)
	v_mfma_f32_32x32x16_bf16 v[32:47], v[152:155], v[204:207], v[32:47]
	ds_read_b128 v[204:207], v188 offset:0x8000
	s_waitcnt lgkmcnt(11)
	v_mfma_f32_32x32x16_bf16 v[32:47], v[148:151], v[208:211], v[32:47]
	ds_read_b128 v[208:211], v188 offset:0xa000
	s_waitcnt lgkmcnt(10)
	v_mfma_f32_32x32x16_bf16 v[16:31], v[160:163], v[212:215], v[16:31]
	ds_read_b128 v[160:163], v187 offset:0x8000
	s_waitcnt lgkmcnt(9)
	v_mfma_f32_32x32x16_bf16 v[16:31], v[156:159], v[216:219], v[16:31]
	ds_read_b128 v[156:159], v187 offset:0xa000
	s_waitcnt lgkmcnt(8)
	v_mfma_f32_32x32x16_bf16 v[16:31], v[152:155], v[220:223], v[16:31]
	ds_read_b128 v[152:155], v184 offset:0x8000
	s_waitcnt lgkmcnt(7)
	v_mfma_f32_32x32x16_bf16 v[16:31], v[148:151], v[224:227], v[16:31]
	ds_read_b128 v[148:151], v184 offset:0xa000
	s_waitcnt lgkmcnt(7)
	v_mfma_f32_32x32x16_bf16 v[80:95], v[196:199], v[144:147], v[80:95]
	ds_read_b128 v[196:199], v182 offset:0x8000
	s_waitcnt lgkmcnt(7)
	v_mfma_f32_32x32x16_bf16 v[64:79], v[200:203], v[144:147], v[64:79]
	ds_read_b128 v[200:203], v182 offset:0xa000
	s_waitcnt lgkmcnt(7)
	v_mfma_f32_32x32x16_bf16 v[80:95], v[204:207], v[136:139], v[80:95]
	ds_read_b128 v[204:207], v183 offset:0x8000
	s_waitcnt lgkmcnt(7)
	v_mfma_f32_32x32x16_bf16 v[64:79], v[208:211], v[136:139], v[64:79]
	ds_read_b128 v[208:211], v183 offset:0xa000
	s_waitcnt lgkmcnt(7)
	v_mfma_f32_32x32x16_bf16 v[80:95], v[160:163], v[128:131], v[80:95]
	ds_read_b128 v[160:163], v185 offset:0x8000
	s_waitcnt lgkmcnt(7)
	v_mfma_f32_32x32x16_bf16 v[64:79], v[156:159], v[128:131], v[64:79]
	ds_read_b128 v[156:159], v185 offset:0xa000
	s_waitcnt lgkmcnt(7)
	v_mfma_f32_32x32x16_bf16 v[80:95], v[152:155], v[124:127], v[80:95]
	ds_read_b128 v[152:155], v186 offset:0x8000
	s_waitcnt lgkmcnt(7)
	v_mfma_f32_32x32x16_bf16 v[64:79], v[148:151], v[124:127], v[64:79]
	ds_read_b128 v[148:151], v186 offset:0xa000
	s_waitcnt lgkmcnt(7)
	v_mfma_f32_32x32x16_bf16 v[80:95], v[196:199], v[120:123], v[80:95]
	s_waitcnt lgkmcnt(6)
	v_mfma_f32_32x32x16_bf16 v[64:79], v[200:203], v[120:123], v[64:79]
	s_waitcnt lgkmcnt(5)
	v_mfma_f32_32x32x16_bf16 v[80:95], v[204:207], v[116:119], v[80:95]
	s_waitcnt lgkmcnt(4)
	v_mfma_f32_32x32x16_bf16 v[64:79], v[208:211], v[116:119], v[64:79]
	s_waitcnt lgkmcnt(3)
	v_mfma_f32_32x32x16_bf16 v[80:95], v[160:163], v[140:143], v[80:95]
	s_waitcnt lgkmcnt(2)
	v_mfma_f32_32x32x16_bf16 v[64:79], v[156:159], v[140:143], v[64:79]
	s_waitcnt lgkmcnt(1)
	v_mfma_f32_32x32x16_bf16 v[80:95], v[152:155], v[132:135], v[80:95]
	s_waitcnt lgkmcnt(0)
	v_mfma_f32_32x32x16_bf16 v[64:79], v[148:151], v[132:135], v[64:79]
	s_setprio 0
	s_waitcnt lgkmcnt(0)
	s_barrier
	s_cmp_le_i32 s84, s78
	s_mov_b64 s[0:1], -1
	s_cbranch_scc0 .LBB0_1340
	s_add_i32 s0, s84, 63
	s_cmp_le_i32 s0, s75
	s_cbranch_scc1 .LBB0_1339
	v_cmp_gt_i32_e64 s[58:59], 26, v193
	v_cmp_gt_i32_e64 s[60:61], 27, v193
	v_cmp_gt_i32_e64 s[56:57], 25, v193
	v_cmp_gt_i32_e64 s[54:55], 24, v193
	v_cmp_gt_i32_e64 s[52:53], 19, v193
	v_cmp_gt_i32_e64 s[50:51], 18, v193
	v_cmp_gt_i32_e64 s[48:49], 17, v193
	v_cmp_gt_i32_e64 s[46:47], 16, v193
	v_cmp_gt_i32_e64 s[44:45], 11, v193
	v_cmp_gt_i32_e64 s[42:43], 10, v193
	v_cmp_gt_i32_e64 s[40:41], 9, v193
	v_cmp_gt_i32_e64 s[38:39], 8, v193
	v_cmp_gt_i32_e64 s[36:37], 3, v193
	v_cmp_gt_i32_e64 s[34:35], 2, v193
	v_cmp_gt_i32_e64 s[30:31], 1, v193
	v_cmp_gt_i32_e64 s[28:29], 0, v193
	v_cmp_gt_i32_e64 s[26:27], 58, v193
	s_nop 1
	v_cndmask_b32_e64 v80, v80, v169, s[28:29]
	v_cmp_gt_i32_e64 s[28:29], 59, v193
	v_cmp_gt_i32_e64 s[24:25], 57, v193
	v_cmp_gt_i32_e64 s[22:23], 56, v193
	v_cmp_gt_i32_e64 s[20:21], 51, v193
	v_cmp_gt_i32_e64 s[18:19], 50, v193
	v_cmp_gt_i32_e64 s[16:17], 49, v193
	v_cmp_gt_i32_e64 s[14:15], 48, v193
	v_cmp_gt_i32_e64 s[12:13], 43, v193
	v_cmp_gt_i32_e64 s[10:11], 42, v193
	v_cmp_gt_i32_e64 s[8:9], 41, v193
	v_cmp_gt_i32_e64 s[6:7], 40, v193
	v_cmp_gt_i32_e64 s[4:5], 35, v193
	v_cmp_gt_i32_e64 s[2:3], 34, v193
	v_cmp_gt_i32_e64 s[0:1], 33, v193
	v_cmp_gt_i32_e32 vcc, 32, v193
	v_cndmask_b32_e64 v95, v95, v169, s[60:61]
	v_cndmask_b32_e64 v94, v94, v169, s[58:59]
	v_cndmask_b32_e64 v93, v93, v169, s[56:57]
	v_cndmask_b32_e64 v92, v92, v169, s[54:55]
	v_cndmask_b32_e64 v91, v91, v169, s[52:53]
	v_cndmask_b32_e64 v90, v90, v169, s[50:51]
	v_cndmask_b32_e64 v89, v89, v169, s[48:49]
	v_cndmask_b32_e64 v88, v88, v169, s[46:47]
	v_cndmask_b32_e64 v87, v87, v169, s[44:45]
	v_cndmask_b32_e64 v86, v86, v169, s[42:43]
	v_cndmask_b32_e64 v85, v85, v169, s[40:41]
	v_cndmask_b32_e64 v84, v84, v169, s[38:39]
	v_cndmask_b32_e64 v83, v83, v169, s[36:37]
	v_cndmask_b32_e64 v82, v82, v169, s[34:35]
	v_cndmask_b32_e64 v81, v81, v169, s[30:31]
	v_cndmask_b32_e64 v79, v79, v169, s[28:29]
	v_cndmask_b32_e64 v78, v78, v169, s[26:27]
	v_cndmask_b32_e64 v77, v77, v169, s[24:25]
	v_cndmask_b32_e64 v76, v76, v169, s[22:23]
	v_cndmask_b32_e64 v75, v75, v169, s[20:21]
	v_cndmask_b32_e64 v74, v74, v169, s[18:19]
	v_cndmask_b32_e64 v73, v73, v169, s[16:17]
	v_cndmask_b32_e64 v72, v72, v169, s[14:15]
	v_cndmask_b32_e64 v71, v71, v169, s[12:13]
	v_cndmask_b32_e64 v70, v70, v169, s[10:11]
	v_cndmask_b32_e64 v69, v69, v169, s[8:9]
	v_cndmask_b32_e64 v68, v68, v169, s[6:7]
	v_cndmask_b32_e64 v67, v67, v169, s[4:5]
	v_cndmask_b32_e64 v66, v66, v169, s[2:3]
	v_cndmask_b32_e64 v65, v65, v169, s[0:1]
	v_cndmask_b32_e32 v64, v64, v169, vcc
	s_nop 0

.LBB0_1350:
	s_setprio 1
	v_lshl_add_u32 v80, s82, 8, v190
	ds_read_b128 v[64:67], v80
	ds_read_b128 v[68:71], v80 offset:32
	ds_read_b128 v[72:75], v80 offset:64
	ds_read_b128 v[76:79], v80 offset:96
	ds_read_b128 v[192:195], v80 offset:128
	ds_read_b128 v[196:199], v80 offset:160
	ds_read_b128 v[200:203], v80 offset:192
	ds_read_b128 v[204:207], v80 offset:224
	s_lshl_b32 s2, s82, 6
	s_waitcnt lgkmcnt(4)
	v_pk_add_f32 v[94:95], v[78:79], v[180:181] op_sel:[0,1] op_sel_hi:[1,1] neg_lo:[0,1] neg_hi:[0,1]
	v_pk_add_f32 v[92:93], v[76:77], v[180:181] op_sel:[0,1] op_sel_hi:[1,1] neg_lo:[0,1] neg_hi:[0,1]
	v_pk_add_f32 v[90:91], v[74:75], v[180:181] op_sel:[0,1] op_sel_hi:[1,1] neg_lo:[0,1] neg_hi:[0,1]
	v_pk_add_f32 v[88:89], v[72:73], v[180:181] op_sel:[0,1] op_sel_hi:[1,1] neg_lo:[0,1] neg_hi:[0,1]
	v_pk_add_f32 v[86:87], v[70:71], v[180:181] op_sel:[0,1] op_sel_hi:[1,1] neg_lo:[0,1] neg_hi:[0,1]
	v_pk_add_f32 v[84:85], v[68:69], v[180:181] op_sel:[0,1] op_sel_hi:[1,1] neg_lo:[0,1] neg_hi:[0,1]
	v_pk_add_f32 v[82:83], v[66:67], v[180:181] op_sel:[0,1] op_sel_hi:[1,1] neg_lo:[0,1] neg_hi:[0,1]
	v_pk_add_f32 v[80:81], v[64:65], v[180:181] op_sel:[0,1] op_sel_hi:[1,1] neg_lo:[0,1] neg_hi:[0,1]
	s_waitcnt lgkmcnt(0)
	v_pk_add_f32 v[78:79], v[206:207], v[180:181] op_sel:[0,1] op_sel_hi:[1,1] neg_lo:[0,1] neg_hi:[0,1]
	v_pk_add_f32 v[76:77], v[204:205], v[180:181] op_sel:[0,1] op_sel_hi:[1,1] neg_lo:[0,1] neg_hi:[0,1]
	v_pk_add_f32 v[74:75], v[202:203], v[180:181] op_sel:[0,1] op_sel_hi:[1,1] neg_lo:[0,1] neg_hi:[0,1]
	v_pk_add_f32 v[72:73], v[200:201], v[180:181] op_sel:[0,1] op_sel_hi:[1,1] neg_lo:[0,1] neg_hi:[0,1]
	v_pk_add_f32 v[70:71], v[198:199], v[180:181] op_sel:[0,1] op_sel_hi:[1,1] neg_lo:[0,1] neg_hi:[0,1]
	v_pk_add_f32 v[68:69], v[196:197], v[180:181] op_sel:[0,1] op_sel_hi:[1,1] neg_lo:[0,1] neg_hi:[0,1]
	v_pk_add_f32 v[66:67], v[194:195], v[180:181] op_sel:[0,1] op_sel_hi:[1,1] neg_lo:[0,1] neg_hi:[0,1]
	v_pk_add_f32 v[64:65], v[192:193], v[180:181] op_sel:[0,1] op_sel_hi:[1,1] neg_lo:[0,1] neg_hi:[0,1]
	ds_read_b64_tr_b16 v[192:193], v179 offset:0
	ds_read_b64_tr_b16 v[194:195], v179 offset:0x800
	ds_read_b64_tr_b16 v[196:197], v179 offset:0x1000
	ds_read_b64_tr_b16 v[198:199], v179 offset:0x1800
	ds_read_b64_tr_b16 v[200:201], v179 offset:0x2000
	ds_read_b64_tr_b16 v[202:203], v179 offset:0x2800
	ds_read_b64_tr_b16 v[204:205], v179 offset:0x3000
	ds_read_b64_tr_b16 v[206:207], v179 offset:0x3800
	ds_read_b64_tr_b16 v[208:209], v179 offset:0x200
	ds_read_b64_tr_b16 v[210:211], v179 offset:0xa00
	ds_read_b64_tr_b16 v[212:213], v179 offset:0x1200
	ds_read_b64_tr_b16 v[214:215], v179 offset:0x1a00
	ds_read_b64_tr_b16 v[216:217], v179 offset:0x2200
	ds_read_b64_tr_b16 v[218:219], v179 offset:0x2a00
	ds_read_b64_tr_b16 v[220:221], v179 offset:0x3200
	ds_read_b64_tr_b16 v[222:223], v179 offset:0x3a00
	s_waitcnt lgkmcnt(14)
	s_nop 0
	v_mfma_f32_32x32x16_bf16 v[0:15], v[160:163], v[192:195], v[0:15]
	ds_read_b64_tr_b16 v[192:193], v179 offset:0x400
	ds_read_b64_tr_b16 v[194:195], v179 offset:0xc00
	s_waitcnt lgkmcnt(14)
	v_mfma_f32_32x32x16_bf16 v[0:15], v[156:159], v[196:199], v[0:15]
	ds_read_b64_tr_b16 v[196:197], v179 offset:0x1400
	ds_read_b64_tr_b16 v[198:199], v179 offset:0x1c00
	s_waitcnt lgkmcnt(14)
	v_mfma_f32_32x32x16_bf16 v[0:15], v[152:155], v[200:203], v[0:15]
	ds_read_b64_tr_b16 v[200:201], v179 offset:0x2400
	ds_read_b64_tr_b16 v[202:203], v179 offset:0x2c00
	s_waitcnt lgkmcnt(14)
	v_mfma_f32_32x32x16_bf16 v[0:15], v[148:151], v[204:207], v[0:15]
	ds_read_b64_tr_b16 v[204:205], v179 offset:0x3400
	ds_read_b64_tr_b16 v[206:207], v179 offset:0x3c00
	s_waitcnt lgkmcnt(14)
	v_mfma_f32_32x32x16_bf16 v[48:63], v[160:163], v[208:211], v[48:63]
	ds_read_b64_tr_b16 v[208:209], v179 offset:0x600
	ds_read_b64_tr_b16 v[210:211], v179 offset:0xe00
	s_waitcnt lgkmcnt(14)
	v_mfma_f32_32x32x16_bf16 v[48:63], v[156:159], v[212:215], v[48:63]
	ds_read_b64_tr_b16 v[212:213], v179 offset:0x1600
	ds_read_b64_tr_b16 v[214:215], v179 offset:0x1e00
	s_waitcnt lgkmcnt(14)
	v_mfma_f32_32x32x16_bf16 v[48:63], v[152:155], v[216:219], v[48:63]
	ds_read_b64_tr_b16 v[216:217], v179 offset:0x2600
	ds_read_b64_tr_b16 v[218:219], v179 offset:0x2e00
	s_waitcnt lgkmcnt(14)
	v_mfma_f32_32x32x16_bf16 v[48:63], v[148:151], v[220:223], v[48:63]
	ds_read_b64_tr_b16 v[220:221], v179 offset:0x3600
	ds_read_b64_tr_b16 v[222:223], v179 offset:0x3e00
	s_waitcnt lgkmcnt(14)
	v_mfma_f32_32x32x16_bf16 v[32:47], v[160:163], v[192:195], v[32:47]
	ds_read_b128 v[192:195], v189 offset:0xc000
	s_waitcnt lgkmcnt(13)
	v_mfma_f32_32x32x16_bf16 v[32:47], v[156:159], v[196:199], v[32:47]
	ds_read_b128 v[196:199], v189 offset:0xe000
	s_waitcnt lgkmcnt(12)
	v_mfma_f32_32x32x16_bf16 v[32:47], v[152:155], v[200:203], v[32:47]
	ds_read_b128 v[200:203], v188 offset:0xc000
	s_waitcnt lgkmcnt(11)
	v_mfma_f32_32x32x16_bf16 v[32:47], v[148:151], v[204:207], v[32:47]
	ds_read_b128 v[204:207], v188 offset:0xe000
	s_waitcnt lgkmcnt(10)
	v_mfma_f32_32x32x16_bf16 v[16:31], v[160:163], v[208:211], v[16:31]
	ds_read_b128 v[160:163], v187 offset:0xc000
	s_waitcnt lgkmcnt(9)
	v_mfma_f32_32x32x16_bf16 v[16:31], v[156:159], v[212:215], v[16:31]
	ds_read_b128 v[156:159], v187 offset:0xe000
	s_waitcnt lgkmcnt(8)
	v_mfma_f32_32x32x16_bf16 v[16:31], v[152:155], v[216:219], v[16:31]
	ds_read_b128 v[152:155], v184 offset:0xc000
	s_waitcnt lgkmcnt(7)
	v_mfma_f32_32x32x16_bf16 v[16:31], v[148:151], v[220:223], v[16:31]
	ds_read_b128 v[148:151], v184 offset:0xe000
	s_waitcnt lgkmcnt(7)
	v_mfma_f32_32x32x16_bf16 v[80:95], v[192:195], v[144:147], v[80:95]
	ds_read_b128 v[192:195], v182 offset:0xc000
	s_waitcnt lgkmcnt(7)
	v_mfma_f32_32x32x16_bf16 v[64:79], v[196:199], v[144:147], v[64:79]
	ds_read_b128 v[144:147], v182 offset:0xe000
	s_waitcnt lgkmcnt(7)
	v_mfma_f32_32x32x16_bf16 v[80:95], v[200:203], v[136:139], v[80:95]
	ds_read_b128 v[196:199], v183 offset:0xc000
	s_waitcnt lgkmcnt(7)
	v_mfma_f32_32x32x16_bf16 v[64:79], v[204:207], v[136:139], v[64:79]
	ds_read_b128 v[136:139], v183 offset:0xe000
	s_waitcnt lgkmcnt(7)
	v_mfma_f32_32x32x16_bf16 v[80:95], v[160:163], v[128:131], v[80:95]
	ds_read_b128 v[160:163], v185 offset:0xc000
	s_waitcnt lgkmcnt(7)
	v_mfma_f32_32x32x16_bf16 v[64:79], v[156:159], v[128:131], v[64:79]
	ds_read_b128 v[128:131], v185 offset:0xe000
	s_waitcnt lgkmcnt(7)
	v_mfma_f32_32x32x16_bf16 v[80:95], v[152:155], v[124:127], v[80:95]
	ds_read_b128 v[152:155], v186 offset:0xc000
	s_waitcnt lgkmcnt(7)
	v_mfma_f32_32x32x16_bf16 v[64:79], v[148:151], v[124:127], v[64:79]
	ds_read_b128 v[124:127], v186 offset:0xe000
	s_waitcnt lgkmcnt(7)
	v_mfma_f32_32x32x16_bf16 v[80:95], v[192:195], v[120:123], v[80:95]
	s_waitcnt lgkmcnt(6)
	v_mfma_f32_32x32x16_bf16 v[64:79], v[144:147], v[120:123], v[64:79]
	s_waitcnt lgkmcnt(5)
	v_mfma_f32_32x32x16_bf16 v[80:95], v[196:199], v[116:119], v[80:95]
	s_waitcnt lgkmcnt(4)
	v_mfma_f32_32x32x16_bf16 v[64:79], v[136:139], v[116:119], v[64:79]
	s_waitcnt lgkmcnt(3)
	v_mfma_f32_32x32x16_bf16 v[80:95], v[160:163], v[140:143], v[80:95]
	s_waitcnt lgkmcnt(2)
	v_mfma_f32_32x32x16_bf16 v[64:79], v[128:131], v[140:143], v[64:79]
	s_waitcnt lgkmcnt(1)
	v_mfma_f32_32x32x16_bf16 v[80:95], v[152:155], v[132:135], v[80:95]
	s_waitcnt lgkmcnt(0)
	v_mfma_f32_32x32x16_bf16 v[64:79], v[124:127], v[132:135], v[64:79]
	s_setprio 0
	s_waitcnt lgkmcnt(0)
	s_barrier
	s_cmp_le_i32 s2, s78
	s_mov_b64 s[0:1], -1
	s_cbranch_scc0 .LBB0_1354
	s_or_b32 s0, s2, 63
	s_cmp_le_i32 s0, s75
	s_cbranch_scc1 .LBB0_1353
	v_subrev_u32_e32 v97, s2, v178
	v_cmp_gt_i32_e64 s[58:59], 26, v97
	v_cmp_gt_i32_e64 s[60:61], 27, v97
	v_cmp_gt_i32_e64 s[56:57], 25, v97
	v_cmp_gt_i32_e64 s[54:55], 24, v97
	v_cmp_gt_i32_e64 s[52:53], 19, v97
	v_cmp_gt_i32_e64 s[50:51], 18, v97
	v_cmp_gt_i32_e64 s[48:49], 17, v97
	v_cmp_gt_i32_e64 s[46:47], 16, v97
	v_cmp_gt_i32_e64 s[44:45], 11, v97
	v_cmp_gt_i32_e64 s[42:43], 10, v97
	v_cmp_gt_i32_e64 s[40:41], 9, v97
	v_cmp_gt_i32_e64 s[38:39], 8, v97
	v_cmp_gt_i32_e64 s[36:37], 3, v97
	v_cmp_gt_i32_e64 s[34:35], 2, v97
	v_cmp_gt_i32_e64 s[30:31], 1, v97
	v_cmp_gt_i32_e64 s[28:29], 0, v97
	v_cmp_gt_i32_e64 s[26:27], 58, v97
	s_nop 1
	v_cndmask_b32_e64 v80, v80, v169, s[28:29]
	v_cmp_gt_i32_e64 s[28:29], 59, v97
	v_cmp_gt_i32_e64 s[24:25], 57, v97
	v_cmp_gt_i32_e64 s[22:23], 56, v97
	v_cmp_gt_i32_e64 s[20:21], 51, v97
	v_cmp_gt_i32_e64 s[18:19], 50, v97
	v_cmp_gt_i32_e64 s[16:17], 49, v97
	v_cmp_gt_i32_e64 s[14:15], 48, v97
	v_cmp_gt_i32_e64 s[12:13], 43, v97
	v_cmp_gt_i32_e64 s[10:11], 42, v97
	v_cmp_gt_i32_e64 s[8:9], 41, v97
	v_cmp_gt_i32_e64 s[6:7], 40, v97
	v_cmp_gt_i32_e64 s[4:5], 35, v97
	v_cmp_gt_i32_e64 s[2:3], 34, v97
	v_cmp_gt_i32_e64 s[0:1], 33, v97
	v_cmp_gt_i32_e32 vcc, 32, v97
	v_cndmask_b32_e64 v95, v95, v169, s[60:61]
	v_cndmask_b32_e64 v94, v94, v169, s[58:59]
	v_cndmask_b32_e64 v93, v93, v169, s[56:57]
	v_cndmask_b32_e64 v92, v92, v169, s[54:55]
	v_cndmask_b32_e64 v91, v91, v169, s[52:53]
	v_cndmask_b32_e64 v90, v90, v169, s[50:51]
	v_cndmask_b32_e64 v89, v89, v169, s[48:49]
	v_cndmask_b32_e64 v88, v88, v169, s[46:47]
	v_cndmask_b32_e64 v87, v87, v169, s[44:45]
	v_cndmask_b32_e64 v86, v86, v169, s[42:43]
	v_cndmask_b32_e64 v85, v85, v169, s[40:41]
	v_cndmask_b32_e64 v84, v84, v169, s[38:39]
	v_cndmask_b32_e64 v83, v83, v169, s[36:37]
	v_cndmask_b32_e64 v82, v82, v169, s[34:35]
	v_cndmask_b32_e64 v81, v81, v169, s[30:31]
	v_cndmask_b32_e64 v79, v79, v169, s[28:29]
	v_cndmask_b32_e64 v78, v78, v169, s[26:27]
	v_cndmask_b32_e64 v77, v77, v169, s[24:25]
	v_cndmask_b32_e64 v76, v76, v169, s[22:23]
	v_cndmask_b32_e64 v75, v75, v169, s[20:21]
	v_cndmask_b32_e64 v74, v74, v169, s[18:19]
	v_cndmask_b32_e64 v73, v73, v169, s[16:17]
	v_cndmask_b32_e64 v72, v72, v169, s[14:15]
	v_cndmask_b32_e64 v71, v71, v169, s[12:13]
	v_cndmask_b32_e64 v70, v70, v169, s[10:11]
	v_cndmask_b32_e64 v69, v69, v169, s[8:9]
	v_cndmask_b32_e64 v68, v68, v169, s[6:7]
	v_cndmask_b32_e64 v67, v67, v169, s[4:5]
	v_cndmask_b32_e64 v66, v66, v169, s[2:3]
	v_cndmask_b32_e64 v65, v65, v169, s[0:1]
	v_cndmask_b32_e32 v64, v64, v169, vcc
	s_nop 0
